# speedup vs baseline: 1.0054x; 1.0054x over previous
; #define STAGE_TILE() do { SW_BEGIN const f32x4 v_ = acc[ai][bj][m][n2]; \
;     *(u32x2*)(smem + mrow * SPITCH + nc0 * 2) = u32x2{cvtpk(v_[0], v_[1]), cvtpk(v_[2], v_[3])}; LOOP_END __syncthreads(); } while (0)
; #define STAGE_TILE_F(XFORM) do { SW_BEGIN f32x4 v = acc[ai][bj][m][n2]; XFORM; \
;     *(u32x2*)(smem + mrow * SPITCH + nc0 * 2) = u32x2{cvtpk_t(v[0], v[1]), cvtpk_t(v[2], v[3])}; LOOP_END __syncthreads(); } while (0)
; template <int kind> __device__ __forceinline__ void gemm_phase_n(const Params& P, int layer, int b, const int wv) {
;     ...
;             case G_OUTP: case G_OUTH: {
;                 if (kind == G_OUTH) STAGE_TILE_F(v *= rs_lds[3 * 256 + mrow]); else STAGE_TILE();
;                 u16* dst = (u16*)(ws + O_Y) + (size_t)(pm * 256) * 1024 + pn * 256;
;                 DRAIN_BEGIN *(u32x4*)(dst + (size_t)row * 1024 + chunk * 8) = w; LOOP_END
.LBB0_371:
	v_mov_b32_e32 v0, v1
	s_movk_i32 s4, 0x60
	v_mbcnt_lo_u32_b32 v0, -1, v0
	v_mbcnt_hi_u32_b32 v0, -1, v0
	v_or_b32_e32 v130, s57, v0
	s_lshl_b64 s[6:7], s[10:11], 1
	v_and_b32_e32 v0, 15, v130
	v_lshrrev_b32_e32 v131, 1, v130
	v_and_or_b32 v131, v131, s4, v0
	v_readlane_b32 s4, v254, 15
	v_lshrrev_b32_e32 v134, 2, v130
	v_ashrrev_i32_e32 v133, 2, v130
	v_lshl_add_u32 v0, v131, 2, s4
	ds_read_b32 v135, v0 offset:3072
	ds_read_b32 v136, v0 offset:3136
	ds_read_b32 v137, v0 offset:3584
	ds_read_b32 v138, v0 offset:3648
	s_waitcnt lgkmcnt(0)
	v_mov_b32_e32 v132, v135
	v_and_b32_e32 v134, 12, v134
	s_mov_b32 s4, 0x7fffffc0
	v_and_or_b32 v133, v133, s4, v134
	v_lshlrev_b32_e32 v134, 1, v133
	v_pk_mul_f32 v[126:127], v[126:127], v[132:133] op_sel_hi:[1,0]
	v_pk_mul_f32 v[128:129], v[128:129], v[132:133] op_sel_hi:[1,0]
	s_nop 0
	v_cvt_pk_bf16_f32 v132, v126, v127
	v_mul_u32_u24_e32 v126, 0x220, v131
	v_add3_u32 v126, 0, v134, v126
	s_nop 0
	v_cvt_pk_bf16_f32 v133, v128, v129
	ds_write_b64 v126, v[132:133]
	v_mov_b32_e32 v128, v136
	s_lshl_b32 s4, s8, 8
	s_ashr_i32 s5, s4, 31
	s_lshl_b64 s[4:5], s[4:5], 11
	s_add_u32 s6, s24, s6
	v_pk_mul_f32 v[122:123], v[122:123], v[128:129] op_sel_hi:[1,0]
	v_pk_mul_f32 v[124:125], v[124:125], v[128:129] op_sel_hi:[1,0]
	s_nop 0
	v_cvt_pk_bf16_f32 v122, v122, v123
	s_movk_i32 s8, 0x220
	s_nop 0
	v_cvt_pk_bf16_f32 v123, v124, v125
	ds_write_b64 v126, v[122:123] offset:8704
	v_mov_b32_e32 v122, v137
	v_add_u32_e32 v123, 0x2200, v126
	s_addc_u32 s7, s25, s7
	v_pk_mul_f32 v[118:119], v[118:119], v[122:123] op_sel_hi:[1,0]
	v_pk_mul_f32 v[120:121], v[120:121], v[122:123] op_sel_hi:[1,0]
	s_nop 0
	v_cvt_pk_bf16_f32 v118, v118, v119
	s_nop 0
	s_nop 0
	v_cvt_pk_bf16_f32 v119, v120, v121
	ds_write_b64 v123, v[118:119] offset:60928
	v_mov_b32_e32 v118, v138
	v_add_u32_e32 v119, 0xee00, v123
	v_pk_mul_f32 v[114:115], v[114:115], v[118:119] op_sel_hi:[1,0]
	v_pk_mul_f32 v[116:117], v[116:117], v[118:119] op_sel_hi:[1,0]
	s_nop 0
	v_cvt_pk_bf16_f32 v114, v114, v115
	s_nop 0
	s_nop 0
	v_cvt_pk_bf16_f32 v115, v116, v117
	ds_write_b64 v119, v[114:115] offset:8704
	s_waitcnt vmcnt(0)
	v_mov_b32_e32 v114, v135
	v_pk_mul_f32 v[110:111], v[110:111], v[114:115] op_sel_hi:[1,0]
	v_pk_mul_f32 v[112:113], v[112:113], v[114:115] op_sel_hi:[1,0]
	s_nop 0
	v_cvt_pk_bf16_f32 v110, v110, v111
	s_nop 0
	s_nop 0
	v_cvt_pk_bf16_f32 v111, v112, v113
	ds_write_b64 v126, v[110:111] offset:32
	v_mov_b32_e32 v110, v136
	v_pk_mul_f32 v[106:107], v[106:107], v[110:111] op_sel_hi:[1,0]
	v_pk_mul_f32 v[108:109], v[108:109], v[110:111] op_sel_hi:[1,0]
	s_nop 0
	v_cvt_pk_bf16_f32 v106, v106, v107
	s_nop 0
	s_nop 0
	v_cvt_pk_bf16_f32 v107, v108, v109
	ds_write_b64 v126, v[106:107] offset:8736
	v_mov_b32_e32 v106, v137
	v_pk_mul_f32 v[102:103], v[102:103], v[106:107] op_sel_hi:[1,0]
	v_pk_mul_f32 v[104:105], v[104:105], v[106:107] op_sel_hi:[1,0]
	s_nop 0
	v_cvt_pk_bf16_f32 v102, v102, v103
	s_nop 0
	s_nop 0
	v_cvt_pk_bf16_f32 v103, v104, v105
	ds_write_b64 v123, v[102:103] offset:60960
	v_mov_b32_e32 v102, v138
	v_pk_mul_f32 v[98:99], v[98:99], v[102:103] op_sel_hi:[1,0]
	v_pk_mul_f32 v[100:101], v[100:101], v[102:103] op_sel_hi:[1,0]
	s_nop 0
	v_cvt_pk_bf16_f32 v98, v98, v99
	s_nop 0
	s_nop 0
	v_cvt_pk_bf16_f32 v99, v100, v101
	ds_write_b64 v119, v[98:99] offset:8736
	v_mov_b32_e32 v98, v135
	v_pk_mul_f32 v[94:95], v[94:95], v[98:99] op_sel_hi:[1,0]
	v_pk_mul_f32 v[96:97], v[96:97], v[98:99] op_sel_hi:[1,0]
	s_nop 0
	v_cvt_pk_bf16_f32 v94, v94, v95
	s_nop 0
	s_nop 0
	v_cvt_pk_bf16_f32 v95, v96, v97
	ds_write_b64 v126, v[94:95] offset:64
	v_mov_b32_e32 v94, v136
	v_pk_mul_f32 v[90:91], v[90:91], v[94:95] op_sel_hi:[1,0]
	v_pk_mul_f32 v[92:93], v[92:93], v[94:95] op_sel_hi:[1,0]
	s_nop 0
	v_cvt_pk_bf16_f32 v90, v90, v91
	s_nop 0
	s_nop 0
	v_cvt_pk_bf16_f32 v91, v92, v93
	ds_write_b64 v126, v[90:91] offset:8768
	v_mov_b32_e32 v90, v137
	v_pk_mul_f32 v[86:87], v[86:87], v[90:91] op_sel_hi:[1,0]
	v_pk_mul_f32 v[88:89], v[88:89], v[90:91] op_sel_hi:[1,0]
	s_nop 0
	v_cvt_pk_bf16_f32 v86, v86, v87
	s_nop 0
	s_nop 0
	v_cvt_pk_bf16_f32 v87, v88, v89
	ds_write_b64 v123, v[86:87] offset:60992
	v_mov_b32_e32 v86, v138
	v_pk_mul_f32 v[82:83], v[82:83], v[86:87] op_sel_hi:[1,0]
	v_pk_mul_f32 v[84:85], v[84:85], v[86:87] op_sel_hi:[1,0]
	s_nop 0
	v_cvt_pk_bf16_f32 v82, v82, v83
	s_nop 0
	s_nop 0
	v_cvt_pk_bf16_f32 v83, v84, v85
	ds_write_b64 v119, v[82:83] offset:8768
	v_mov_b32_e32 v82, v135
	v_pk_mul_f32 v[78:79], v[78:79], v[82:83] op_sel_hi:[1,0]
	v_pk_mul_f32 v[80:81], v[80:81], v[82:83] op_sel_hi:[1,0]
	s_nop 0
	v_cvt_pk_bf16_f32 v78, v78, v79
	s_nop 0
	s_nop 0
	v_cvt_pk_bf16_f32 v79, v80, v81
	ds_write_b64 v126, v[78:79] offset:96
	v_mov_b32_e32 v78, v136
	v_pk_mul_f32 v[74:75], v[74:75], v[78:79] op_sel_hi:[1,0]
	v_pk_mul_f32 v[76:77], v[76:77], v[78:79] op_sel_hi:[1,0]
	s_nop 0
	v_cvt_pk_bf16_f32 v74, v74, v75
	s_nop 0
	s_nop 0
	v_cvt_pk_bf16_f32 v75, v76, v77
	ds_write_b64 v126, v[74:75] offset:8800
	v_mov_b32_e32 v74, v137
	v_pk_mul_f32 v[70:71], v[70:71], v[74:75] op_sel_hi:[1,0]
	v_pk_mul_f32 v[72:73], v[72:73], v[74:75] op_sel_hi:[1,0]
	s_nop 0
	v_cvt_pk_bf16_f32 v70, v70, v71
; #define STAGE_TILE() do { SW_BEGIN const f32x4 v_ = acc[ai][bj][m][n2]; \
;     *(u32x2*)(smem + mrow * SPITCH + nc0 * 2) = u32x2{cvtpk(v_[0], v_[1]), cvtpk(v_[2], v_[3])}; LOOP_END __syncthreads(); } while (0)
; #define STAGE_TILE_F(XFORM) do { SW_BEGIN f32x4 v = acc[ai][bj][m][n2]; XFORM; \
;     *(u32x2*)(smem + mrow * SPITCH + nc0 * 2) = u32x2{cvtpk_t(v[0], v[1]), cvtpk_t(v[2], v[3])}; LOOP_END __syncthreads(); } while (0)
; template <int kind> __device__ __forceinline__ void gemm_phase_n(const Params& P, int layer, int b, const int wv) {
;     ...
;             case G_OUTP: case G_OUTH: {
;                 if (kind == G_OUTH) STAGE_TILE_F(v *= rs_lds[3 * 256 + mrow]); else STAGE_TILE();
;                 u16* dst = (u16*)(ws + O_Y) + (size_t)(pm * 256) * 1024 + pn * 256;
;                 DRAIN_BEGIN *(u32x4*)(dst + (size_t)row * 1024 + chunk * 8) = w; LOOP_END
	s_nop 0
	s_nop 0
	v_cvt_pk_bf16_f32 v71, v72, v73
	ds_write_b64 v123, v[70:71] offset:61024
	v_mov_b32_e32 v70, v138
	v_pk_mul_f32 v[66:67], v[66:67], v[70:71] op_sel_hi:[1,0]
	v_pk_mul_f32 v[68:69], v[68:69], v[70:71] op_sel_hi:[1,0]
	s_nop 0
	v_cvt_pk_bf16_f32 v66, v66, v67
	s_nop 0
	s_nop 0
	v_cvt_pk_bf16_f32 v67, v68, v69
	ds_write_b64 v119, v[66:67] offset:8800
	v_mov_b32_e32 v66, v135
	v_pk_mul_f32 v[62:63], v[62:63], v[66:67] op_sel_hi:[1,0]
	v_pk_mul_f32 v[64:65], v[64:65], v[66:67] op_sel_hi:[1,0]
	s_nop 0
	v_cvt_pk_bf16_f32 v62, v62, v63
	s_nop 0
	s_nop 0
	v_cvt_pk_bf16_f32 v63, v64, v65
	ds_write_b64 v126, v[62:63] offset:256
	v_mov_b32_e32 v62, v136
	v_pk_mul_f32 v[58:59], v[58:59], v[62:63] op_sel_hi:[1,0]
	v_pk_mul_f32 v[60:61], v[60:61], v[62:63] op_sel_hi:[1,0]
	s_nop 0
	v_cvt_pk_bf16_f32 v58, v58, v59
	s_nop 0
	s_nop 0
	v_cvt_pk_bf16_f32 v59, v60, v61
	ds_write_b64 v126, v[58:59] offset:8960
	v_mov_b32_e32 v58, v137
	v_pk_mul_f32 v[54:55], v[54:55], v[58:59] op_sel_hi:[1,0]
	v_pk_mul_f32 v[56:57], v[56:57], v[58:59] op_sel_hi:[1,0]
	s_nop 0
	v_cvt_pk_bf16_f32 v54, v54, v55
	s_nop 0
	s_nop 0
	v_cvt_pk_bf16_f32 v55, v56, v57
	ds_write_b64 v123, v[54:55] offset:61184
	v_mov_b32_e32 v54, v138
	v_pk_mul_f32 v[50:51], v[50:51], v[54:55] op_sel_hi:[1,0]
	v_pk_mul_f32 v[52:53], v[52:53], v[54:55] op_sel_hi:[1,0]
	s_nop 0
	v_cvt_pk_bf16_f32 v50, v50, v51
	s_nop 0
	s_nop 0
	v_cvt_pk_bf16_f32 v51, v52, v53
	ds_write_b64 v119, v[50:51] offset:8960
	v_mov_b32_e32 v50, v135
	v_pk_mul_f32 v[46:47], v[46:47], v[50:51] op_sel_hi:[1,0]
	v_pk_mul_f32 v[48:49], v[48:49], v[50:51] op_sel_hi:[1,0]
	s_nop 0
	v_cvt_pk_bf16_f32 v46, v46, v47
	s_nop 0
	s_nop 0
	v_cvt_pk_bf16_f32 v47, v48, v49
	ds_write_b64 v126, v[46:47] offset:288
	v_mov_b32_e32 v46, v136
	v_pk_mul_f32 v[42:43], v[42:43], v[46:47] op_sel_hi:[1,0]
	v_pk_mul_f32 v[44:45], v[44:45], v[46:47] op_sel_hi:[1,0]
	s_nop 0
	v_cvt_pk_bf16_f32 v42, v42, v43
	s_nop 0
	s_nop 0
	v_cvt_pk_bf16_f32 v43, v44, v45
	ds_write_b64 v126, v[42:43] offset:8992
	v_mov_b32_e32 v42, v137
	v_pk_mul_f32 v[38:39], v[38:39], v[42:43] op_sel_hi:[1,0]
	v_pk_mul_f32 v[40:41], v[40:41], v[42:43] op_sel_hi:[1,0]
	s_nop 0
	v_cvt_pk_bf16_f32 v38, v38, v39
	s_nop 0
	s_nop 0
	v_cvt_pk_bf16_f32 v39, v40, v41
	ds_write_b64 v123, v[38:39] offset:61216
	v_mov_b32_e32 v38, v138
	v_pk_mul_f32 v[34:35], v[34:35], v[38:39] op_sel_hi:[1,0]
	v_pk_mul_f32 v[36:37], v[36:37], v[38:39] op_sel_hi:[1,0]
	s_nop 0
	v_cvt_pk_bf16_f32 v34, v34, v35
	s_nop 0
	s_nop 0
	v_cvt_pk_bf16_f32 v35, v36, v37
	ds_write_b64 v119, v[34:35] offset:8992
	v_mov_b32_e32 v34, v135
	v_pk_mul_f32 v[30:31], v[30:31], v[34:35] op_sel_hi:[1,0]
	v_pk_mul_f32 v[32:33], v[32:33], v[34:35] op_sel_hi:[1,0]
	s_nop 0
	v_cvt_pk_bf16_f32 v30, v30, v31
	s_nop 0
	s_nop 0
	v_cvt_pk_bf16_f32 v31, v32, v33
	ds_write_b64 v126, v[30:31] offset:320
	v_mov_b32_e32 v30, v136
	v_pk_mul_f32 v[26:27], v[26:27], v[30:31] op_sel_hi:[1,0]
	v_pk_mul_f32 v[28:29], v[28:29], v[30:31] op_sel_hi:[1,0]
	s_nop 0
	v_cvt_pk_bf16_f32 v26, v26, v27
	s_nop 0
	s_nop 0
	v_cvt_pk_bf16_f32 v27, v28, v29
	ds_write_b64 v126, v[26:27] offset:9024
	v_mov_b32_e32 v26, v137
	v_pk_mul_f32 v[22:23], v[22:23], v[26:27] op_sel_hi:[1,0]
	v_pk_mul_f32 v[24:25], v[24:25], v[26:27] op_sel_hi:[1,0]
	s_nop 0
	v_cvt_pk_bf16_f32 v22, v22, v23
	s_nop 0
	s_nop 0
	v_cvt_pk_bf16_f32 v23, v24, v25
	ds_write_b64 v123, v[22:23] offset:61248
	v_mov_b32_e32 v22, v138
	v_pk_mul_f32 v[18:19], v[18:19], v[22:23] op_sel_hi:[1,0]
	v_pk_mul_f32 v[20:21], v[20:21], v[22:23] op_sel_hi:[1,0]
	s_nop 0
	v_cvt_pk_bf16_f32 v18, v18, v19
	s_nop 0
	s_nop 0
	v_cvt_pk_bf16_f32 v19, v20, v21
	ds_write_b64 v119, v[18:19] offset:9024
	v_mov_b32_e32 v18, v135
	v_pk_mul_f32 v[14:15], v[14:15], v[18:19] op_sel_hi:[1,0]
	v_pk_mul_f32 v[16:17], v[16:17], v[18:19] op_sel_hi:[1,0]
	s_nop 0
	v_cvt_pk_bf16_f32 v14, v14, v15
	s_nop 0
	s_nop 0
	v_cvt_pk_bf16_f32 v15, v16, v17
	ds_write_b64 v126, v[14:15] offset:352
	v_mov_b32_e32 v14, v136
	v_lshlrev_b32_e32 v15, 4, v130
	v_ashrrev_i32_e32 v16, 5, v130
	v_ashrrev_i32_e32 v17, 31, v16
	v_pk_mul_f32 v[10:11], v[10:11], v[14:15] op_sel_hi:[1,0]
	v_pk_mul_f32 v[12:13], v[12:13], v[14:15] op_sel_hi:[1,0]
	s_nop 0
	v_cvt_pk_bf16_f32 v10, v10, v11
	v_mul_lo_u32 v14, v16, s8
	s_nop 0
	v_cvt_pk_bf16_f32 v11, v12, v13
	ds_write_b64 v126, v[10:11] offset:9056
	v_mov_b32_e32 v10, v137
	v_and_b32_e32 v11, 0x1f0, v15
	v_lshlrev_b64 v[12:13], 11, v[16:17]
	v_pk_mul_f32 v[6:7], v[6:7], v[10:11] op_sel_hi:[1,0]
	v_pk_mul_f32 v[8:9], v[8:9], v[10:11] op_sel_hi:[1,0]
	s_nop 0
	v_cvt_pk_bf16_f32 v6, v6, v7
	s_nop 0
	s_nop 0
	v_cvt_pk_bf16_f32 v7, v8, v9
	ds_write_b64 v123, v[6:7] offset:61280
	v_mov_b32_e32 v8, v138
	v_lshl_add_u64 v[6:7], v[12:13], 0, s[4:5]
	v_or_b32_e32 v6, v6, v11
	v_add3_u32 v0, v14, v11, 0
	v_lshl_add_u64 v[6:7], s[6:7], 0, v[6:7]
	v_pk_mul_f32 v[2:3], v[2:3], v[8:9] op_sel_hi:[1,0]
	s_mov_b64 s[4:5], 0
	v_pk_mul_f32 v[4:5], v[4:5], v[8:9] op_sel_hi:[1,0]
	s_nop 0
	v_cvt_pk_bf16_f32 v2, v2, v3
	s_nop 0
	s_nop 0
	v_cvt_pk_bf16_f32 v3, v4, v5
	ds_write_b64 v119, v[2:3] offset:9056
	s_waitcnt lgkmcnt(0)
	s_barrier

; #define STAGE_TILE_F(XFORM) do { SW_BEGIN f32x4 v = acc[ai][bj][m][n2]; XFORM; \
;     *(u32x2*)(smem + mrow * SPITCH + nc0 * 2) = u32x2{cvtpk_t(v[0], v[1]), cvtpk_t(v[2], v[3])}; LOOP_END __syncthreads(); } while (0)
; template <int kind> __device__ __forceinline__ void gemm_phase_n(const Params& P, int layer, int b, const int wv) {
;     ...
;                 } else {
;                     STAGE_TILE_F(v *= rs_lds[mrow]);
;                     u16* base = sub == 0 ? (u16*)(ws + O_QN) : (pn < 8 ? (u16*)(ws + O_KN) : (u16*)(ws + O_V));
;                     const int hb = (pn & 7) * 2;
;                     DRAIN_BEGIN const int h = hb + (chunk >> 4);
;                         *(u32x4*)(base + ((size_t)h * S + s0 + row) * 128 + (chunk & 15) * 8) = w; LOOP_END
.LBB0_592:
	s_or_b64 exec, exec, s[2:3]
	v_mov_b32_e32 v0, v1
	v_cmp_gt_i32_e32 vcc, 8, v137
	v_mbcnt_lo_u32_b32 v0, -1, v0
	v_mbcnt_hi_u32_b32 v0, -1, v0
	v_or_b32_e32 v0, s57, v0
	s_xor_b64 s[2:3], s[4:5], -1
	v_bfe_u32 v131, v0, 6, 2
	v_and_b32_e32 v130, 15, v0
	v_ashrrev_i32_e32 v133, 8, v0
	v_bfe_u32 v146, v0, 4, 2
	v_lshlrev_b32_e32 v134, 8, v145
	s_or_b64 s[2:3], s[2:3], vcc
	v_lshl_or_b32 v135, v131, 5, v130
	s_and_saveexec_b64 s[16:17], s[2:3]
	s_xor_b64 s[2:3], exec, s[16:17]
	s_cbranch_execz .LBB0_595
	v_lshl_add_u32 v131, v135, 2, 0
	v_add_u32_e32 v131, 0x22000, v131
	ds_read_b32 v139, v131
	ds_read_b32 v140, v131 offset:64
	ds_read_b32 v141, v131 offset:512
	ds_read_b32 v142, v131 offset:576
	s_waitcnt lgkmcnt(0)
	v_mov_b32_e32 v132, v139
	v_lshlrev_b32_e32 v136, 7, v133
	v_lshl_add_u32 v138, v146, 3, 0
	v_cmp_gt_i32_e32 vcc, 8, v137
	v_pk_mul_f32 v[126:127], v[126:127], v[132:133] op_sel_hi:[1,0]
	v_pk_mul_f32 v[128:129], v[128:129], v[132:133] op_sel_hi:[1,0]
	s_nop 0
	v_cvt_pk_bf16_f32 v132, v126, v127
	v_mul_u32_u24_e32 v126, 0x220, v135
	v_add3_u32 v126, v138, v136, v126
	s_nop 0
	v_cvt_pk_bf16_f32 v133, v128, v129
	ds_write_b64 v126, v[132:133]
	v_mov_b32_e32 v128, v140
	v_ashrrev_i32_e32 v135, 31, v134
	v_pk_mul_f32 v[106:107], v[106:107], v[128:129] op_sel_hi:[1,0]
	v_pk_mul_f32 v[108:109], v[108:109], v[128:129] op_sel_hi:[1,0]
	s_nop 0
	v_cvt_pk_bf16_f32 v106, v106, v107
	s_nop 0
	s_nop 0
	v_cvt_pk_bf16_f32 v107, v108, v109
	ds_write_b64 v126, v[106:107] offset:8704
	v_mov_b32_e32 v108, v141
	v_add_u32_e32 v106, 0x2200, v126
	v_pk_mul_f32 v[82:83], v[82:83], v[108:109] op_sel_hi:[1,0]
	v_pk_mul_f32 v[84:85], v[84:85], v[108:109] op_sel_hi:[1,0]
	s_nop 0
	v_cvt_pk_bf16_f32 v82, v82, v83
	s_nop 0
	s_nop 0
	v_cvt_pk_bf16_f32 v83, v84, v85
	ds_write_b64 v106, v[82:83] offset:60928
	v_mov_b32_e32 v84, v142
	v_add_u32_e32 v82, 0xee00, v106
	v_pk_mul_f32 v[50:51], v[50:51], v[84:85] op_sel_hi:[1,0]
	v_pk_mul_f32 v[52:53], v[52:53], v[84:85] op_sel_hi:[1,0]
	s_nop 0
	v_cvt_pk_bf16_f32 v50, v50, v51
	s_nop 0
	s_nop 0
	v_cvt_pk_bf16_f32 v51, v52, v53
	ds_write_b64 v82, v[50:51] offset:8704
	s_waitcnt vmcnt(0)
	v_mov_b32_e32 v50, v139
	v_pk_mul_f32 v[52:53], v[120:121], v[50:51] op_sel_hi:[1,0]
	v_pk_mul_f32 v[50:51], v[118:119], v[50:51] op_sel_hi:[1,0]
	s_nop 0
	s_nop 0
	v_cvt_pk_bf16_f32 v50, v50, v51
	s_nop 0
	v_cvt_pk_bf16_f32 v51, v52, v53
	ds_write_b64 v126, v[50:51] offset:32
	v_mov_b32_e32 v50, v140
	v_pk_mul_f32 v[52:53], v[96:97], v[50:51] op_sel_hi:[1,0]
	v_pk_mul_f32 v[50:51], v[94:95], v[50:51] op_sel_hi:[1,0]
	s_nop 0
	s_nop 0
	v_cvt_pk_bf16_f32 v50, v50, v51
	s_nop 0
	v_cvt_pk_bf16_f32 v51, v52, v53
	ds_write_b64 v126, v[50:51] offset:8736
	v_mov_b32_e32 v50, v141
	v_pk_mul_f32 v[52:53], v[64:65], v[50:51] op_sel_hi:[1,0]
	v_pk_mul_f32 v[50:51], v[62:63], v[50:51] op_sel_hi:[1,0]
	s_nop 0
	s_nop 0
	v_cvt_pk_bf16_f32 v50, v50, v51
	s_nop 0
	v_cvt_pk_bf16_f32 v51, v52, v53
	ds_write_b64 v106, v[50:51] offset:60960
	v_mov_b32_e32 v50, v142
	v_pk_mul_f32 v[30:31], v[30:31], v[50:51] op_sel_hi:[1,0]
	v_pk_mul_f32 v[32:33], v[32:33], v[50:51] op_sel_hi:[1,0]
	s_nop 0
	v_cvt_pk_bf16_f32 v30, v30, v31
	s_nop 0
	s_nop 0
	v_cvt_pk_bf16_f32 v31, v32, v33
	ds_write_b64 v82, v[30:31] offset:8736
	v_mov_b32_e32 v30, v139
	v_pk_mul_f32 v[32:33], v[112:113], v[30:31] op_sel_hi:[1,0]
	v_pk_mul_f32 v[30:31], v[110:111], v[30:31] op_sel_hi:[1,0]
	s_nop 0
	s_nop 0
	v_cvt_pk_bf16_f32 v30, v30, v31
	s_nop 0
	v_cvt_pk_bf16_f32 v31, v32, v33
	ds_write_b64 v126, v[30:31] offset:64
	v_mov_b32_e32 v30, v140
	v_pk_mul_f32 v[32:33], v[88:89], v[30:31] op_sel_hi:[1,0]
	v_pk_mul_f32 v[30:31], v[86:87], v[30:31] op_sel_hi:[1,0]
	s_nop 0
	s_nop 0
	v_cvt_pk_bf16_f32 v30, v30, v31
	s_nop 0
	v_cvt_pk_bf16_f32 v31, v32, v33
	ds_write_b64 v126, v[30:31] offset:8768
	v_mov_b32_e32 v30, v141
	v_pk_mul_f32 v[32:33], v[56:57], v[30:31] op_sel_hi:[1,0]
	v_pk_mul_f32 v[30:31], v[54:55], v[30:31] op_sel_hi:[1,0]
	s_nop 0
	s_nop 0
	v_cvt_pk_bf16_f32 v30, v30, v31
	s_nop 0
	v_cvt_pk_bf16_f32 v31, v32, v33
	ds_write_b64 v106, v[30:31] offset:60992
	v_mov_b32_e32 v30, v142
	v_pk_mul_f32 v[22:23], v[22:23], v[30:31] op_sel_hi:[1,0]
	v_pk_mul_f32 v[24:25], v[24:25], v[30:31] op_sel_hi:[1,0]
	s_nop 0
	v_cvt_pk_bf16_f32 v22, v22, v23
	s_nop 0
	s_nop 0
	v_cvt_pk_bf16_f32 v23, v24, v25
	ds_write_b64 v82, v[22:23] offset:8768
	v_mov_b32_e32 v22, v139
	v_pk_mul_f32 v[24:25], v[104:105], v[22:23] op_sel_hi:[1,0]
	v_pk_mul_f32 v[22:23], v[102:103], v[22:23] op_sel_hi:[1,0]
	s_nop 0
	s_nop 0
	v_cvt_pk_bf16_f32 v22, v22, v23
	s_nop 0
	v_cvt_pk_bf16_f32 v23, v24, v25
	ds_write_b64 v126, v[22:23] offset:96
	v_mov_b32_e32 v22, v140
	v_pk_mul_f32 v[24:25], v[76:77], v[22:23] op_sel_hi:[1,0]
	v_pk_mul_f32 v[22:23], v[74:75], v[22:23] op_sel_hi:[1,0]
	s_nop 0
	s_nop 0
	v_cvt_pk_bf16_f32 v22, v22, v23
	s_nop 0
	v_cvt_pk_bf16_f32 v23, v24, v25
	ds_write_b64 v126, v[22:23] offset:8800
	v_mov_b32_e32 v22, v141
	v_pk_mul_f32 v[24:25], v[44:45], v[22:23] op_sel_hi:[1,0]
	v_pk_mul_f32 v[22:23], v[42:43], v[22:23] op_sel_hi:[1,0]
	s_nop 0
	s_nop 0
	v_cvt_pk_bf16_f32 v22, v22, v23
	s_nop 0
	v_cvt_pk_bf16_f32 v23, v24, v25
	ds_write_b64 v106, v[22:23] offset:61024
	v_mov_b32_e32 v22, v142
	v_pk_mul_f32 v[14:15], v[14:15], v[22:23] op_sel_hi:[1,0]
; #define STAGE_TILE_F(XFORM) do { SW_BEGIN f32x4 v = acc[ai][bj][m][n2]; XFORM; \
;     *(u32x2*)(smem + mrow * SPITCH + nc0 * 2) = u32x2{cvtpk_t(v[0], v[1]), cvtpk_t(v[2], v[3])}; LOOP_END __syncthreads(); } while (0)
; template <int kind> __device__ __forceinline__ void gemm_phase_n(const Params& P, int layer, int b, const int wv) {
;     ...
;                 } else {
;                     STAGE_TILE_F(v *= rs_lds[mrow]);
;                     u16* base = sub == 0 ? (u16*)(ws + O_QN) : (pn < 8 ? (u16*)(ws + O_KN) : (u16*)(ws + O_V));
;                     const int hb = (pn & 7) * 2;
;                     DRAIN_BEGIN const int h = hb + (chunk >> 4);
;                         *(u32x4*)(base + ((size_t)h * S + s0 + row) * 128 + (chunk & 15) * 8) = w; LOOP_END
	v_pk_mul_f32 v[16:17], v[16:17], v[22:23] op_sel_hi:[1,0]
	s_nop 0
	v_cvt_pk_bf16_f32 v14, v14, v15
	s_nop 0
	s_nop 0
	v_cvt_pk_bf16_f32 v15, v16, v17
	ds_write_b64 v82, v[14:15] offset:8800
	v_mov_b32_e32 v14, v139
	v_pk_mul_f32 v[16:17], v[124:125], v[14:15] op_sel_hi:[1,0]
	v_pk_mul_f32 v[14:15], v[122:123], v[14:15] op_sel_hi:[1,0]
	s_nop 0
	s_nop 0
	v_cvt_pk_bf16_f32 v14, v14, v15
	s_nop 0
	v_cvt_pk_bf16_f32 v15, v16, v17
	ds_write_b64 v126, v[14:15] offset:256
	v_mov_b32_e32 v14, v140
	v_pk_mul_f32 v[16:17], v[92:93], v[14:15] op_sel_hi:[1,0]
	v_pk_mul_f32 v[14:15], v[90:91], v[14:15] op_sel_hi:[1,0]
	s_nop 0
	s_nop 0
	v_cvt_pk_bf16_f32 v14, v14, v15
	s_nop 0
	v_cvt_pk_bf16_f32 v15, v16, v17
	ds_write_b64 v126, v[14:15] offset:8960
	v_mov_b32_e32 v14, v141
	v_pk_mul_f32 v[16:17], v[60:61], v[14:15] op_sel_hi:[1,0]
	v_pk_mul_f32 v[14:15], v[58:59], v[14:15] op_sel_hi:[1,0]
	s_nop 0
	s_nop 0
	v_cvt_pk_bf16_f32 v14, v14, v15
	s_nop 0
	v_cvt_pk_bf16_f32 v15, v16, v17
	ds_write_b64 v106, v[14:15] offset:61184
	v_mov_b32_e32 v14, v142
	v_pk_mul_f32 v[16:17], v[28:29], v[14:15] op_sel_hi:[1,0]
	v_pk_mul_f32 v[14:15], v[26:27], v[14:15] op_sel_hi:[1,0]
	s_nop 0
	s_nop 0
	v_cvt_pk_bf16_f32 v14, v14, v15
	s_nop 0
	v_cvt_pk_bf16_f32 v15, v16, v17
	ds_write_b64 v82, v[14:15] offset:8960
	v_mov_b32_e32 v14, v139
	v_pk_mul_f32 v[16:17], v[116:117], v[14:15] op_sel_hi:[1,0]
	v_pk_mul_f32 v[14:15], v[114:115], v[14:15] op_sel_hi:[1,0]
	s_nop 0
	s_nop 0
	v_cvt_pk_bf16_f32 v14, v14, v15
	s_nop 0
	v_cvt_pk_bf16_f32 v15, v16, v17
	ds_write_b64 v126, v[14:15] offset:288
	v_mov_b32_e32 v14, v140
	v_pk_mul_f32 v[16:17], v[80:81], v[14:15] op_sel_hi:[1,0]
	v_pk_mul_f32 v[14:15], v[78:79], v[14:15] op_sel_hi:[1,0]
	s_nop 0
	s_nop 0
	v_cvt_pk_bf16_f32 v14, v14, v15
	s_nop 0
	v_cvt_pk_bf16_f32 v15, v16, v17
	ds_write_b64 v126, v[14:15] offset:8992
	v_mov_b32_e32 v14, v141
	v_pk_mul_f32 v[16:17], v[48:49], v[14:15] op_sel_hi:[1,0]
	v_pk_mul_f32 v[14:15], v[46:47], v[14:15] op_sel_hi:[1,0]
	s_nop 0
	s_nop 0
	v_cvt_pk_bf16_f32 v14, v14, v15
	s_nop 0
	v_cvt_pk_bf16_f32 v15, v16, v17
	ds_write_b64 v106, v[14:15] offset:61216
	v_mov_b32_e32 v14, v142
	v_pk_mul_f32 v[16:17], v[20:21], v[14:15] op_sel_hi:[1,0]
	v_pk_mul_f32 v[14:15], v[18:19], v[14:15] op_sel_hi:[1,0]
	v_and_b32_e32 v18, 31, v0
	s_nop 0
	v_cvt_pk_bf16_f32 v14, v14, v15
	s_nop 0
	v_cvt_pk_bf16_f32 v15, v16, v17
	ds_write_b64 v82, v[14:15] offset:8992
	v_mov_b32_e32 v14, v139
	v_bfe_u32 v19, v0, 4, 1
	v_lshlrev_b32_e32 v18, 4, v18
	v_pk_mul_f32 v[16:17], v[100:101], v[14:15] op_sel_hi:[1,0]
	v_pk_mul_f32 v[14:15], v[98:99], v[14:15] op_sel_hi:[1,0]
	s_nop 0
	s_nop 0
	v_cvt_pk_bf16_f32 v14, v14, v15
	s_nop 0
	v_cvt_pk_bf16_f32 v15, v16, v17
	ds_write_b64 v126, v[14:15] offset:320
	v_mov_b32_e32 v14, v140
	v_pk_mul_f32 v[16:17], v[68:69], v[14:15] op_sel_hi:[1,0]
	v_pk_mul_f32 v[14:15], v[66:67], v[14:15] op_sel_hi:[1,0]
	s_nop 0
	s_nop 0
	v_cvt_pk_bf16_f32 v14, v14, v15
	s_nop 0
	v_cvt_pk_bf16_f32 v15, v16, v17
	ds_write_b64 v126, v[14:15] offset:9024
	v_mov_b32_e32 v14, v141
	v_pk_mul_f32 v[16:17], v[36:37], v[14:15] op_sel_hi:[1,0]
	v_pk_mul_f32 v[14:15], v[34:35], v[14:15] op_sel_hi:[1,0]
	s_nop 0
	s_nop 0
	v_cvt_pk_bf16_f32 v14, v14, v15
	s_nop 0
	v_cvt_pk_bf16_f32 v15, v16, v17
	ds_write_b64 v106, v[14:15] offset:61248
	v_mov_b32_e32 v14, v142
	v_mov_b32_e32 v15, 0x1d980000
	v_mov_b32_e32 v16, 0x1b980000
	v_cndmask_b32_e32 v15, v15, v16, vcc
	v_ashrrev_i32_e32 v16, 5, v0
	v_pk_mul_f32 v[6:7], v[6:7], v[14:15] op_sel_hi:[1,0]
	v_pk_mul_f32 v[8:9], v[8:9], v[14:15] op_sel_hi:[1,0]
	s_nop 0
	v_cvt_pk_bf16_f32 v6, v6, v7
	v_mov_b32_e32 v0, 0x18980000
	s_nop 0
	v_cvt_pk_bf16_f32 v7, v8, v9
	ds_write_b64 v82, v[6:7] offset:9024
	v_mov_b32_e32 v6, v139
	v_mov_b32_e32 v7, v1
	v_cndmask_b32_e64 v0, v15, v0, s[4:5]
	v_lshlrev_b32_e32 v17, 1, v137
	v_and_or_b32 v19, v17, 14, v19
	v_pk_mul_f32 v[14:15], v[70:71], v[6:7] op_sel_hi:[1,0]
	v_pk_mul_f32 v[8:9], v[72:73], v[6:7] op_sel_hi:[1,0]
	s_nop 0
	v_cvt_pk_bf16_f32 v14, v14, v15
	v_ashrrev_i32_e32 v17, 31, v16
	s_nop 0
	v_cvt_pk_bf16_f32 v15, v8, v9
	ds_write_b64 v126, v[14:15] offset:352
	v_mov_b32_e32 v6, v140
	s_movk_i32 s4, 0x220
	v_mul_lo_u32 v20, v16, s4
	v_add3_u32 v132, v20, v18, 0
	s_mov_b64 s[4:5], 0
	v_pk_mul_f32 v[14:15], v[38:39], v[6:7] op_sel_hi:[1,0]
	v_pk_mul_f32 v[8:9], v[40:41], v[6:7] op_sel_hi:[1,0]
	s_nop 0
	v_cvt_pk_bf16_f32 v14, v14, v15
	v_lshlrev_b32_e32 v6, 13, v19
	s_nop 0
	v_cvt_pk_bf16_f32 v15, v8, v9
	ds_write_b64 v126, v[14:15] offset:9056
	v_mov_b32_e32 v8, v141
	v_lshl_add_u64 v[14:15], v[16:17], 0, v[134:135]
	v_lshl_add_u64 v[6:7], v[14:15], 0, v[6:7]
	v_lshlrev_b64 v[6:7], 8, v[6:7]
	v_lshl_add_u64 v[6:7], v[0:1], 0, v[6:7]
	v_pk_mul_f32 v[12:13], v[12:13], v[8:9] op_sel_hi:[1,0]
	v_pk_mul_f32 v[8:9], v[10:11], v[8:9] op_sel_hi:[1,0]
	v_lshl_or_b32 v6, v130, 4, v6
	s_nop 0
	v_cvt_pk_bf16_f32 v8, v8, v9
	s_nop 0
	v_cvt_pk_bf16_f32 v9, v12, v13
	ds_write_b64 v106, v[8:9] offset:61280
	v_mov_b32_e32 v8, v142
	v_lshl_add_u64 v[130:131], s[6:7], 0, v[6:7]
	v_pk_mul_f32 v[2:3], v[2:3], v[8:9] op_sel_hi:[1,0]
	v_pk_mul_f32 v[4:5], v[4:5], v[8:9] op_sel_hi:[1,0]
	s_nop 0
	v_cvt_pk_bf16_f32 v2, v2, v3
	s_nop 0
	s_nop 0
	v_cvt_pk_bf16_f32 v3, v4, v5
	ds_write_b64 v82, v[2:3] offset:9056
	s_waitcnt lgkmcnt(0)
	s_barrier

; #define STAGE_TILE_F(XFORM) do { SW_BEGIN f32x4 v = acc[ai][bj][m][n2]; XFORM; \
;     *(u32x2*)(smem + mrow * SPITCH + nc0 * 2) = u32x2{cvtpk_t(v[0], v[1]), cvtpk_t(v[2], v[3])}; LOOP_END __syncthreads(); } while (0)
; template <int kind> __device__ __forceinline__ void gemm_phase_n(const Params& P, int layer, int b, const int wv) {
;     ...
;                 if (pn < 4) {
;                     STAGE_TILE_F(v *= rs_lds[mrow]);
;                     u16* dst = (pn < 3) ? (u16*)(ws + O_CQ) + (size_t)s0 * 768 + pn * 256 : (u16*)(ws + O_CKV) + (size_t)s0 * 256; const int ldd = pn < 3 ? 768 : 256;
;                     float* ssp = pn < 3 ? (float*)(ws + O_CQSS) + (size_t)t0 * 16 + pn * 4 : (float*)(ws + O_CKVSS) + (size_t)t0 * 4; const int sst = pn < 3 ? 16 : 4;
;                     DRAIN_BEGIN *(u32x4*)(dst + (size_t)row * ldd + chunk * 8) = w;
.LBB0_686:
	s_andn2_b64 vcc, exec, s[2:3]
	s_cbranch_vccnz .LBB0_666
	v_lshl_or_b32 v132, v140, 5, v141
	v_lshl_add_u32 v0, v132, 2, 0
	v_add_u32_e32 v133, 0x22000, v0
	ds_read_b32 v134, v133
	ds_read_b32 v135, v133 offset:64
	ds_read_b32 v136, v133 offset:512
	ds_read_b32 v138, v133 offset:576
	s_waitcnt lgkmcnt(0)
	v_mov_b32_e32 v0, v134
	v_lshlrev_b32_e32 v130, 7, v142
	v_lshl_add_u32 v131, v143, 3, 0
	s_lshr_b32 s2, s13, 24
	s_cmp_lg_u32 s2, 3
	v_pk_mul_f32 v[128:129], v[128:129], v[0:1] op_sel_hi:[1,0]
	v_pk_mul_f32 v[126:127], v[126:127], v[0:1] op_sel_hi:[1,0]
	v_mul_u32_u24_e32 v0, 0x220, v132
	s_nop 0
	v_cvt_pk_bf16_f32 v126, v126, v127
	s_nop 0
	v_cvt_pk_bf16_f32 v127, v128, v129
	v_add3_u32 v128, v131, v130, v0
	ds_write_b64 v128, v[126:127]
	v_mov_b32_e32 v0, v135
	v_add_u32_e32 v126, 0x2200, v128
	s_cselect_b64 s[2:3], -1, 0
	s_ashr_i32 s13, s12, 31
	s_mov_b64 s[18:19], -1
	v_pk_mul_f32 v[118:119], v[118:119], v[0:1] op_sel_hi:[1,0]
	v_pk_mul_f32 v[120:121], v[120:121], v[0:1] op_sel_hi:[1,0]
	s_nop 0
	v_cvt_pk_bf16_f32 v118, v118, v119
	s_and_b64 vcc, exec, s[2:3]
	s_nop 0
	v_cvt_pk_bf16_f32 v119, v120, v121
	ds_write_b64 v128, v[118:119] offset:8704
	v_mov_b32_e32 v0, v136
	v_pk_mul_f32 v[120:121], v[122:123], v[0:1] op_sel_hi:[1,0]
	v_pk_mul_f32 v[118:119], v[124:125], v[0:1] op_sel_hi:[1,0]
	s_nop 0
	v_cvt_pk_bf16_f32 v120, v120, v121
	s_nop 0
	s_nop 0
	v_cvt_pk_bf16_f32 v121, v118, v119
	ds_write_b64 v126, v[120:121] offset:60928
	v_mov_b32_e32 v0, v138
	v_add_u32_e32 v118, 0xee00, v126
	v_pk_mul_f32 v[114:115], v[114:115], v[0:1] op_sel_hi:[1,0]
	v_pk_mul_f32 v[116:117], v[116:117], v[0:1] op_sel_hi:[1,0]
	s_nop 0
	v_cvt_pk_bf16_f32 v114, v114, v115
	s_nop 0
	s_nop 0
	v_cvt_pk_bf16_f32 v115, v116, v117
	ds_write_b64 v118, v[114:115] offset:8704
	s_waitcnt vmcnt(0)
	v_mov_b32_e32 v0, v134
	v_pk_mul_f32 v[110:111], v[110:111], v[0:1] op_sel_hi:[1,0]
	v_pk_mul_f32 v[112:113], v[112:113], v[0:1] op_sel_hi:[1,0]
	s_nop 0
	v_cvt_pk_bf16_f32 v110, v110, v111
	s_nop 0
	s_nop 0
	v_cvt_pk_bf16_f32 v111, v112, v113
	ds_write_b64 v128, v[110:111] offset:32
	v_mov_b32_e32 v0, v135
	v_pk_mul_f32 v[102:103], v[102:103], v[0:1] op_sel_hi:[1,0]
	v_pk_mul_f32 v[104:105], v[104:105], v[0:1] op_sel_hi:[1,0]
	s_nop 0
	v_cvt_pk_bf16_f32 v102, v102, v103
	s_nop 0
	s_nop 0
	v_cvt_pk_bf16_f32 v103, v104, v105
	ds_write_b64 v128, v[102:103] offset:8736
	v_mov_b32_e32 v0, v136
	v_pk_mul_f32 v[104:105], v[106:107], v[0:1] op_sel_hi:[1,0]
	v_pk_mul_f32 v[102:103], v[108:109], v[0:1] op_sel_hi:[1,0]
	s_nop 0
	v_cvt_pk_bf16_f32 v104, v104, v105
	s_nop 0
	s_nop 0
	v_cvt_pk_bf16_f32 v105, v102, v103
	ds_write_b64 v126, v[104:105] offset:60960
	v_mov_b32_e32 v0, v138
	v_pk_mul_f32 v[98:99], v[98:99], v[0:1] op_sel_hi:[1,0]
	v_pk_mul_f32 v[100:101], v[100:101], v[0:1] op_sel_hi:[1,0]
	s_nop 0
	v_cvt_pk_bf16_f32 v98, v98, v99
	s_nop 0
	s_nop 0
	v_cvt_pk_bf16_f32 v99, v100, v101
	ds_write_b64 v118, v[98:99] offset:8736
	v_mov_b32_e32 v0, v134
	v_pk_mul_f32 v[94:95], v[94:95], v[0:1] op_sel_hi:[1,0]
	v_pk_mul_f32 v[96:97], v[96:97], v[0:1] op_sel_hi:[1,0]
	s_nop 0
	v_cvt_pk_bf16_f32 v94, v94, v95
	s_nop 0
	s_nop 0
	v_cvt_pk_bf16_f32 v95, v96, v97
	ds_write_b64 v128, v[94:95] offset:64
	v_mov_b32_e32 v0, v135
	v_pk_mul_f32 v[86:87], v[86:87], v[0:1] op_sel_hi:[1,0]
	v_pk_mul_f32 v[88:89], v[88:89], v[0:1] op_sel_hi:[1,0]
	s_nop 0
	v_cvt_pk_bf16_f32 v86, v86, v87
	s_nop 0
	s_nop 0
	v_cvt_pk_bf16_f32 v87, v88, v89
	ds_write_b64 v128, v[86:87] offset:8768
	v_mov_b32_e32 v0, v136
	v_pk_mul_f32 v[88:89], v[90:91], v[0:1] op_sel_hi:[1,0]
	v_pk_mul_f32 v[86:87], v[92:93], v[0:1] op_sel_hi:[1,0]
	s_nop 0
	v_cvt_pk_bf16_f32 v88, v88, v89
	s_nop 0
	s_nop 0
	v_cvt_pk_bf16_f32 v89, v86, v87
	ds_write_b64 v126, v[88:89] offset:60992
	v_mov_b32_e32 v0, v138
	v_pk_mul_f32 v[82:83], v[82:83], v[0:1] op_sel_hi:[1,0]
	v_pk_mul_f32 v[84:85], v[84:85], v[0:1] op_sel_hi:[1,0]
	s_nop 0
	v_cvt_pk_bf16_f32 v82, v82, v83
	s_nop 0
	s_nop 0
	v_cvt_pk_bf16_f32 v83, v84, v85
	ds_write_b64 v118, v[82:83] offset:8768
	v_mov_b32_e32 v0, v134
	v_pk_mul_f32 v[78:79], v[78:79], v[0:1] op_sel_hi:[1,0]
	v_pk_mul_f32 v[80:81], v[80:81], v[0:1] op_sel_hi:[1,0]
	s_nop 0
	v_cvt_pk_bf16_f32 v78, v78, v79
	s_nop 0
	s_nop 0
	v_cvt_pk_bf16_f32 v79, v80, v81
	ds_write_b64 v128, v[78:79] offset:96
	v_mov_b32_e32 v0, v135
	v_pk_mul_f32 v[70:71], v[70:71], v[0:1] op_sel_hi:[1,0]
	v_pk_mul_f32 v[72:73], v[72:73], v[0:1] op_sel_hi:[1,0]
	s_nop 0
	v_cvt_pk_bf16_f32 v70, v70, v71
	s_nop 0
	s_nop 0
	v_cvt_pk_bf16_f32 v71, v72, v73
	ds_write_b64 v128, v[70:71] offset:8800
	v_mov_b32_e32 v0, v136
	v_pk_mul_f32 v[72:73], v[74:75], v[0:1] op_sel_hi:[1,0]
	v_pk_mul_f32 v[70:71], v[76:77], v[0:1] op_sel_hi:[1,0]
	s_nop 0
	v_cvt_pk_bf16_f32 v72, v72, v73
	s_nop 0
	s_nop 0
; #define STAGE_TILE_F(XFORM) do { SW_BEGIN f32x4 v = acc[ai][bj][m][n2]; XFORM; \
;     *(u32x2*)(smem + mrow * SPITCH + nc0 * 2) = u32x2{cvtpk_t(v[0], v[1]), cvtpk_t(v[2], v[3])}; LOOP_END __syncthreads(); } while (0)
; template <int kind> __device__ __forceinline__ void gemm_phase_n(const Params& P, int layer, int b, const int wv) {
;     ...
;                 if (pn < 4) {
;                     STAGE_TILE_F(v *= rs_lds[mrow]);
;                     u16* dst = (pn < 3) ? (u16*)(ws + O_CQ) + (size_t)s0 * 768 + pn * 256 : (u16*)(ws + O_CKV) + (size_t)s0 * 256; const int ldd = pn < 3 ? 768 : 256;
;                     float* ssp = pn < 3 ? (float*)(ws + O_CQSS) + (size_t)t0 * 16 + pn * 4 : (float*)(ws + O_CKVSS) + (size_t)t0 * 4; const int sst = pn < 3 ? 16 : 4;
;                     DRAIN_BEGIN *(u32x4*)(dst + (size_t)row * ldd + chunk * 8) = w;
	v_cvt_pk_bf16_f32 v73, v70, v71
	ds_write_b64 v126, v[72:73] offset:61024
	v_mov_b32_e32 v0, v138
	v_pk_mul_f32 v[62:63], v[62:63], v[0:1] op_sel_hi:[1,0]
	v_pk_mul_f32 v[64:65], v[64:65], v[0:1] op_sel_hi:[1,0]
	s_nop 0
	v_cvt_pk_bf16_f32 v62, v62, v63
	s_nop 0
	s_nop 0
	v_cvt_pk_bf16_f32 v63, v64, v65
	ds_write_b64 v118, v[62:63] offset:8800
	v_mov_b32_e32 v0, v134
	v_pk_mul_f32 v[64:65], v[66:67], v[0:1] op_sel_hi:[1,0]
	v_pk_mul_f32 v[62:63], v[68:69], v[0:1] op_sel_hi:[1,0]
	s_nop 0
	v_cvt_pk_bf16_f32 v64, v64, v65
	s_nop 0
	s_nop 0
	v_cvt_pk_bf16_f32 v65, v62, v63
	ds_write_b64 v128, v[64:65] offset:256
	v_mov_b32_e32 v0, v135
	v_pk_mul_f32 v[54:55], v[54:55], v[0:1] op_sel_hi:[1,0]
	v_pk_mul_f32 v[56:57], v[56:57], v[0:1] op_sel_hi:[1,0]
	s_nop 0
	v_cvt_pk_bf16_f32 v54, v54, v55
	s_nop 0
	s_nop 0
	v_cvt_pk_bf16_f32 v55, v56, v57
	ds_write_b64 v128, v[54:55] offset:8960
	v_mov_b32_e32 v0, v136
	v_pk_mul_f32 v[56:57], v[58:59], v[0:1] op_sel_hi:[1,0]
	v_pk_mul_f32 v[54:55], v[60:61], v[0:1] op_sel_hi:[1,0]
	s_nop 0
	v_cvt_pk_bf16_f32 v56, v56, v57
	s_nop 0
	s_nop 0
	v_cvt_pk_bf16_f32 v57, v54, v55
	ds_write_b64 v126, v[56:57] offset:61184
	v_mov_b32_e32 v0, v138
	v_pk_mul_f32 v[50:51], v[50:51], v[0:1] op_sel_hi:[1,0]
	v_pk_mul_f32 v[52:53], v[52:53], v[0:1] op_sel_hi:[1,0]
	s_nop 0
	v_cvt_pk_bf16_f32 v50, v50, v51
	s_nop 0
	s_nop 0
	v_cvt_pk_bf16_f32 v51, v52, v53
	ds_write_b64 v118, v[50:51] offset:8960
	v_mov_b32_e32 v0, v134
	v_pk_mul_f32 v[46:47], v[46:47], v[0:1] op_sel_hi:[1,0]
	v_pk_mul_f32 v[48:49], v[48:49], v[0:1] op_sel_hi:[1,0]
	s_nop 0
	v_cvt_pk_bf16_f32 v46, v46, v47
	s_nop 0
	s_nop 0
	v_cvt_pk_bf16_f32 v47, v48, v49
	ds_write_b64 v128, v[46:47] offset:288
	v_mov_b32_e32 v0, v135
	v_pk_mul_f32 v[38:39], v[38:39], v[0:1] op_sel_hi:[1,0]
	v_pk_mul_f32 v[40:41], v[40:41], v[0:1] op_sel_hi:[1,0]
	s_nop 0
	v_cvt_pk_bf16_f32 v38, v38, v39
	s_nop 0
	s_nop 0
	v_cvt_pk_bf16_f32 v39, v40, v41
	ds_write_b64 v128, v[38:39] offset:8992
	v_mov_b32_e32 v0, v136
	v_pk_mul_f32 v[40:41], v[42:43], v[0:1] op_sel_hi:[1,0]
	v_pk_mul_f32 v[38:39], v[44:45], v[0:1] op_sel_hi:[1,0]
	s_nop 0
	v_cvt_pk_bf16_f32 v40, v40, v41
	s_nop 0
	s_nop 0
	v_cvt_pk_bf16_f32 v41, v38, v39
	ds_write_b64 v126, v[40:41] offset:61216
	v_mov_b32_e32 v0, v138
	v_pk_mul_f32 v[34:35], v[34:35], v[0:1] op_sel_hi:[1,0]
	v_pk_mul_f32 v[36:37], v[36:37], v[0:1] op_sel_hi:[1,0]
	s_nop 0
	v_cvt_pk_bf16_f32 v34, v34, v35
	s_nop 0
	s_nop 0
	v_cvt_pk_bf16_f32 v35, v36, v37
	ds_write_b64 v118, v[34:35] offset:8992
	v_mov_b32_e32 v0, v134
	v_pk_mul_f32 v[30:31], v[30:31], v[0:1] op_sel_hi:[1,0]
	v_pk_mul_f32 v[32:33], v[32:33], v[0:1] op_sel_hi:[1,0]
	s_nop 0
	v_cvt_pk_bf16_f32 v30, v30, v31
	s_nop 0
	s_nop 0
	v_cvt_pk_bf16_f32 v31, v32, v33
	ds_write_b64 v128, v[30:31] offset:320
	v_mov_b32_e32 v0, v135
	v_pk_mul_f32 v[22:23], v[22:23], v[0:1] op_sel_hi:[1,0]
	v_pk_mul_f32 v[24:25], v[24:25], v[0:1] op_sel_hi:[1,0]
	s_nop 0
	v_cvt_pk_bf16_f32 v22, v22, v23
	s_nop 0
	s_nop 0
	v_cvt_pk_bf16_f32 v23, v24, v25
	ds_write_b64 v128, v[22:23] offset:9024
	v_mov_b32_e32 v0, v136
	v_pk_mul_f32 v[24:25], v[26:27], v[0:1] op_sel_hi:[1,0]
	v_pk_mul_f32 v[22:23], v[28:29], v[0:1] op_sel_hi:[1,0]
	s_nop 0
	v_cvt_pk_bf16_f32 v24, v24, v25
	s_nop 0
	s_nop 0
	v_cvt_pk_bf16_f32 v25, v22, v23
	ds_write_b64 v126, v[24:25] offset:61248
	v_mov_b32_e32 v0, v138
	v_pk_mul_f32 v[18:19], v[18:19], v[0:1] op_sel_hi:[1,0]
	v_pk_mul_f32 v[20:21], v[20:21], v[0:1] op_sel_hi:[1,0]
	s_nop 0
	v_cvt_pk_bf16_f32 v18, v18, v19
	s_nop 0
	s_nop 0
	v_cvt_pk_bf16_f32 v19, v20, v21
	ds_write_b64 v118, v[18:19] offset:9024
	v_mov_b32_e32 v0, v134
	v_pk_mul_f32 v[14:15], v[14:15], v[0:1] op_sel_hi:[1,0]
	v_pk_mul_f32 v[16:17], v[16:17], v[0:1] op_sel_hi:[1,0]
	s_nop 0
	v_cvt_pk_bf16_f32 v14, v14, v15
	s_nop 0
	s_nop 0
	v_cvt_pk_bf16_f32 v15, v16, v17
	ds_write_b64 v128, v[14:15] offset:352
	v_mov_b32_e32 v0, v135
	v_pk_mul_f32 v[2:3], v[2:3], v[0:1] op_sel_hi:[1,0]
	v_pk_mul_f32 v[4:5], v[4:5], v[0:1] op_sel_hi:[1,0]
	s_nop 0
	v_cvt_pk_bf16_f32 v2, v2, v3
	s_nop 0
	s_nop 0
	v_cvt_pk_bf16_f32 v3, v4, v5
	ds_write_b64 v128, v[2:3] offset:9056
	v_mov_b32_e32 v0, v136
	v_pk_mul_f32 v[4:5], v[10:11], v[0:1] op_sel_hi:[1,0]
	v_pk_mul_f32 v[2:3], v[12:13], v[0:1] op_sel_hi:[1,0]
	s_nop 0
	v_cvt_pk_bf16_f32 v4, v4, v5
	s_nop 0
	s_nop 0
	v_cvt_pk_bf16_f32 v5, v2, v3
	ds_write_b64 v126, v[4:5] offset:61280
	v_mov_b32_e32 v0, v138
	v_pk_mul_f32 v[4:5], v[6:7], v[0:1] op_sel_hi:[1,0]
	v_pk_mul_f32 v[2:3], v[8:9], v[0:1] op_sel_hi:[1,0]
	s_nop 0
	v_cvt_pk_bf16_f32 v4, v4, v5
	s_nop 0
	s_nop 0
	v_cvt_pk_bf16_f32 v5, v2, v3
	ds_write_b64 v118, v[4:5] offset:9056
	s_waitcnt lgkmcnt(0)
	s_barrier
	s_cbranch_vccnz .LBB0_702
	s_andn2_b64 vcc, exec, s[18:19]
	s_mov_b64 s[14:15], 0x300
	s_cbranch_vccz .LBB0_703

; #define STAGE_TILE_F(XFORM) do { SW_BEGIN f32x4 v = acc[ai][bj][m][n2]; XFORM; \
;     *(u32x2*)(smem + mrow * SPITCH + nc0 * 2) = u32x2{cvtpk_t(v[0], v[1]), cvtpk_t(v[2], v[3])}; LOOP_END __syncthreads(); } while (0)
; template <int kind> __device__ __forceinline__ void gemm_phase_n(const Params& P, int layer, int b, const int wv) {
;     ...
;                 } else if (pn < 16) {
;                     const int h = (pn - 8) >> 1, half = (pn - 8) & 1, item = h * 32 + pm;
;                     STAGE_TILE_F(v *= rs_lds[mrow]);
;                     u16* VS = (u16*)(ws + O_VS) + ((size_t)item * 512 + half * 256) * 512; TDRAIN(VS, 512);
.LBB0_724:
	s_and_b64 vcc, exec, s[2:3]
	s_mov_b64 s[14:15], 0x80
	s_cbranch_vccz .LBB0_727
	v_lshl_or_b32 v141, v136, 5, v135
	v_lshl_add_u32 v0, v141, 2, 0
	v_add_u32_e32 v142, 0x22000, v0
	ds_read_b32 v143, v142
	ds_read_b32 v144, v142 offset:64
	ds_read_b32 v145, v142 offset:512
	ds_read_b32 v146, v142 offset:576
	s_waitcnt lgkmcnt(0)
	v_mov_b32_e32 v0, v143
	v_lshlrev_b32_e32 v137, 7, v133
	v_lshl_add_u32 v140, v134, 3, 0
	s_movk_i32 s3, 0x1100
	s_lshl_b32 s2, s34, 4
	v_pk_mul_f32 v[130:131], v[124:125], v[0:1] op_sel_hi:[1,0]
	v_pk_mul_f32 v[138:139], v[122:123], v[0:1] op_sel_hi:[1,0]
	v_mul_u32_u24_e32 v0, 0x220, v141
	v_add3_u32 v137, v140, v137, v0
	s_nop 0
	v_cvt_pk_bf16_f32 v138, v138, v139
	s_nop 0
	v_cvt_pk_bf16_f32 v139, v130, v131
	ds_write_b64 v137, v[138:139]
	v_mov_b32_e32 v0, v144
	v_add_u32_e32 v140, 0x2200, v137
	v_add_u32_e32 v141, 0xee00, v140
	s_and_b32 s2, s2, 0xe0
	s_add_i32 s2, s2, s29
	v_pk_mul_f32 v[138:139], v[90:91], v[0:1] op_sel_hi:[1,0]
	v_pk_mul_f32 v[130:131], v[92:93], v[0:1] op_sel_hi:[1,0]
	s_nop 0
	v_cvt_pk_bf16_f32 v138, v138, v139
	s_and_b32 s5, s35, 1
	s_nop 0
	v_cvt_pk_bf16_f32 v139, v130, v131
	ds_write_b64 v137, v[138:139] offset:8704
	v_mov_b32_e32 v0, v145
	s_lshl_b32 s5, s5, 18
	v_pk_mul_f32 v[138:139], v[58:59], v[0:1] op_sel_hi:[1,0]
	v_pk_mul_f32 v[130:131], v[60:61], v[0:1] op_sel_hi:[1,0]
	s_nop 0
	v_cvt_pk_bf16_f32 v138, v138, v139
	s_nop 0
	s_nop 0
	v_cvt_pk_bf16_f32 v139, v130, v131
	ds_write_b64 v140, v[138:139] offset:60928
	v_mov_b32_e32 v0, v146
	v_pk_mul_f32 v[138:139], v[26:27], v[0:1] op_sel_hi:[1,0]
	v_pk_mul_f32 v[130:131], v[28:29], v[0:1] op_sel_hi:[1,0]
	s_nop 0
	v_cvt_pk_bf16_f32 v138, v138, v139
	s_nop 0
	s_nop 0
	v_cvt_pk_bf16_f32 v139, v130, v131
	ds_write_b64 v141, v[138:139] offset:8704
	s_waitcnt vmcnt(0)
	v_mov_b32_e32 v0, v143
	v_pk_mul_f32 v[138:139], v[114:115], v[0:1] op_sel_hi:[1,0]
	v_pk_mul_f32 v[130:131], v[116:117], v[0:1] op_sel_hi:[1,0]
	s_nop 0
	v_cvt_pk_bf16_f32 v138, v138, v139
	s_nop 0
	s_nop 0
	v_cvt_pk_bf16_f32 v139, v130, v131
	ds_write_b64 v137, v[138:139] offset:32
	v_mov_b32_e32 v0, v144
	v_pk_mul_f32 v[138:139], v[82:83], v[0:1] op_sel_hi:[1,0]
	v_pk_mul_f32 v[130:131], v[84:85], v[0:1] op_sel_hi:[1,0]
	s_nop 0
	v_cvt_pk_bf16_f32 v138, v138, v139
	s_nop 0
	s_nop 0
	v_cvt_pk_bf16_f32 v139, v130, v131
	ds_write_b64 v137, v[138:139] offset:8736
	v_mov_b32_e32 v0, v145
	v_pk_mul_f32 v[138:139], v[50:51], v[0:1] op_sel_hi:[1,0]
	v_pk_mul_f32 v[130:131], v[52:53], v[0:1] op_sel_hi:[1,0]
	s_nop 0
	v_cvt_pk_bf16_f32 v138, v138, v139
	s_nop 0
	s_nop 0
	v_cvt_pk_bf16_f32 v139, v130, v131
	ds_write_b64 v140, v[138:139] offset:60960
	v_mov_b32_e32 v0, v146
	v_pk_mul_f32 v[138:139], v[18:19], v[0:1] op_sel_hi:[1,0]
	v_pk_mul_f32 v[130:131], v[20:21], v[0:1] op_sel_hi:[1,0]
	s_nop 0
	v_cvt_pk_bf16_f32 v138, v138, v139
	s_nop 0
	s_nop 0
	v_cvt_pk_bf16_f32 v139, v130, v131
	ds_write_b64 v141, v[138:139] offset:8736
	v_mov_b32_e32 v0, v143
	v_pk_mul_f32 v[138:139], v[102:103], v[0:1] op_sel_hi:[1,0]
	v_pk_mul_f32 v[130:131], v[104:105], v[0:1] op_sel_hi:[1,0]
	s_nop 0
	v_cvt_pk_bf16_f32 v138, v138, v139
	s_nop 0
	s_nop 0
	v_cvt_pk_bf16_f32 v139, v130, v131
	ds_write_b64 v137, v[138:139] offset:64
	v_mov_b32_e32 v0, v144
	v_pk_mul_f32 v[138:139], v[70:71], v[0:1] op_sel_hi:[1,0]
	v_pk_mul_f32 v[130:131], v[72:73], v[0:1] op_sel_hi:[1,0]
	s_nop 0
	v_cvt_pk_bf16_f32 v138, v138, v139
	s_nop 0
	s_nop 0
	v_cvt_pk_bf16_f32 v139, v130, v131
	ds_write_b64 v137, v[138:139] offset:8768
	v_mov_b32_e32 v0, v145
	v_pk_mul_f32 v[138:139], v[38:39], v[0:1] op_sel_hi:[1,0]
	v_pk_mul_f32 v[130:131], v[40:41], v[0:1] op_sel_hi:[1,0]
	s_nop 0
	v_cvt_pk_bf16_f32 v138, v138, v139
	s_nop 0
	s_nop 0
	v_cvt_pk_bf16_f32 v139, v130, v131
	ds_write_b64 v140, v[138:139] offset:60992
	v_mov_b32_e32 v0, v146
	v_pk_mul_f32 v[138:139], v[10:11], v[0:1] op_sel_hi:[1,0]
	v_pk_mul_f32 v[130:131], v[12:13], v[0:1] op_sel_hi:[1,0]
	s_nop 0
	v_cvt_pk_bf16_f32 v138, v138, v139
	s_nop 0
	s_nop 0
	v_cvt_pk_bf16_f32 v139, v130, v131
	ds_write_b64 v141, v[138:139] offset:8768
	v_mov_b32_e32 v0, v143
	v_pk_mul_f32 v[138:139], v[98:99], v[0:1] op_sel_hi:[1,0]
	v_pk_mul_f32 v[130:131], v[100:101], v[0:1] op_sel_hi:[1,0]
	s_nop 0
	v_cvt_pk_bf16_f32 v138, v138, v139
	s_nop 0
	s_nop 0
	v_cvt_pk_bf16_f32 v139, v130, v131
	ds_write_b64 v137, v[138:139] offset:96
	v_mov_b32_e32 v0, v144
	v_pk_mul_f32 v[138:139], v[66:67], v[0:1] op_sel_hi:[1,0]
	v_pk_mul_f32 v[130:131], v[68:69], v[0:1] op_sel_hi:[1,0]
	s_nop 0
	v_cvt_pk_bf16_f32 v138, v138, v139
	s_nop 0
	s_nop 0
	v_cvt_pk_bf16_f32 v139, v130, v131
	ds_write_b64 v137, v[138:139] offset:8800
	v_mov_b32_e32 v0, v145
	v_pk_mul_f32 v[138:139], v[34:35], v[0:1] op_sel_hi:[1,0]
	v_pk_mul_f32 v[130:131], v[36:37], v[0:1] op_sel_hi:[1,0]
	s_nop 0
	v_cvt_pk_bf16_f32 v138, v138, v139
	s_nop 0
	s_nop 0
	v_cvt_pk_bf16_f32 v139, v130, v131
	ds_write_b64 v140, v[138:139] offset:61024
	v_mov_b32_e32 v0, v146
	v_pk_mul_f32 v[138:139], v[2:3], v[0:1] op_sel_hi:[1,0]
	v_pk_mul_f32 v[130:131], v[4:5], v[0:1] op_sel_hi:[1,0]
	s_nop 0
	v_cvt_pk_bf16_f32 v138, v138, v139
	s_nop 0
	s_nop 0
	v_cvt_pk_bf16_f32 v139, v130, v131
	ds_write_b64 v141, v[138:139] offset:8800
; #define STAGE_TILE_F(XFORM) do { SW_BEGIN f32x4 v = acc[ai][bj][m][n2]; XFORM; \
;     *(u32x2*)(smem + mrow * SPITCH + nc0 * 2) = u32x2{cvtpk_t(v[0], v[1]), cvtpk_t(v[2], v[3])}; LOOP_END __syncthreads(); } while (0)
; template <int kind> __device__ __forceinline__ void gemm_phase_n(const Params& P, int layer, int b, const int wv) {
;     ...
;                 } else if (pn < 16) {
;                     const int h = (pn - 8) >> 1, half = (pn - 8) & 1, item = h * 32 + pm;
;                     STAGE_TILE_F(v *= rs_lds[mrow]);
;                     u16* VS = (u16*)(ws + O_VS) + ((size_t)item * 512 + half * 256) * 512; TDRAIN(VS, 512);
	v_mov_b32_e32 v0, v143
	v_pk_mul_f32 v[138:139], v[126:127], v[0:1] op_sel_hi:[1,0]
	v_pk_mul_f32 v[130:131], v[128:129], v[0:1] op_sel_hi:[1,0]
	s_nop 0
	v_cvt_pk_bf16_f32 v138, v138, v139
	s_nop 0
	s_nop 0
	v_cvt_pk_bf16_f32 v139, v130, v131
	ds_write_b64 v137, v[138:139] offset:256
	v_mov_b32_e32 v0, v144
	v_pk_mul_f32 v[138:139], v[94:95], v[0:1] op_sel_hi:[1,0]
	v_pk_mul_f32 v[130:131], v[96:97], v[0:1] op_sel_hi:[1,0]
	s_nop 0
	v_cvt_pk_bf16_f32 v138, v138, v139
	s_nop 0
	s_nop 0
	v_cvt_pk_bf16_f32 v139, v130, v131
	ds_write_b64 v137, v[138:139] offset:8960
	v_mov_b32_e32 v0, v145
	v_pk_mul_f32 v[138:139], v[62:63], v[0:1] op_sel_hi:[1,0]
	v_pk_mul_f32 v[130:131], v[64:65], v[0:1] op_sel_hi:[1,0]
	s_nop 0
	v_cvt_pk_bf16_f32 v138, v138, v139
	s_nop 0
	s_nop 0
	v_cvt_pk_bf16_f32 v139, v130, v131
	ds_write_b64 v140, v[138:139] offset:61184
	v_mov_b32_e32 v0, v146
	v_pk_mul_f32 v[138:139], v[30:31], v[0:1] op_sel_hi:[1,0]
	v_pk_mul_f32 v[130:131], v[32:33], v[0:1] op_sel_hi:[1,0]
	s_nop 0
	v_cvt_pk_bf16_f32 v138, v138, v139
	s_nop 0
	s_nop 0
	v_cvt_pk_bf16_f32 v139, v130, v131
	ds_write_b64 v141, v[138:139] offset:8960
	v_mov_b32_e32 v0, v143
	v_pk_mul_f32 v[138:139], v[118:119], v[0:1] op_sel_hi:[1,0]
	v_pk_mul_f32 v[130:131], v[120:121], v[0:1] op_sel_hi:[1,0]
	s_nop 0
	v_cvt_pk_bf16_f32 v138, v138, v139
	s_nop 0
	s_nop 0
	v_cvt_pk_bf16_f32 v139, v130, v131
	ds_write_b64 v137, v[138:139] offset:288
	v_mov_b32_e32 v0, v144
	v_pk_mul_f32 v[138:139], v[86:87], v[0:1] op_sel_hi:[1,0]
	v_pk_mul_f32 v[130:131], v[88:89], v[0:1] op_sel_hi:[1,0]
	s_nop 0
	v_cvt_pk_bf16_f32 v138, v138, v139
	s_nop 0
	s_nop 0
	v_cvt_pk_bf16_f32 v139, v130, v131
	ds_write_b64 v137, v[138:139] offset:8992
	v_mov_b32_e32 v0, v145
	v_pk_mul_f32 v[138:139], v[54:55], v[0:1] op_sel_hi:[1,0]
	v_pk_mul_f32 v[130:131], v[56:57], v[0:1] op_sel_hi:[1,0]
	s_nop 0
	v_cvt_pk_bf16_f32 v138, v138, v139
	s_nop 0
	s_nop 0
	v_cvt_pk_bf16_f32 v139, v130, v131
	ds_write_b64 v140, v[138:139] offset:61216
	v_mov_b32_e32 v0, v146
	v_pk_mul_f32 v[138:139], v[22:23], v[0:1] op_sel_hi:[1,0]
	v_pk_mul_f32 v[130:131], v[24:25], v[0:1] op_sel_hi:[1,0]
	s_nop 0
	v_cvt_pk_bf16_f32 v138, v138, v139
	s_nop 0
	s_nop 0
	v_cvt_pk_bf16_f32 v139, v130, v131
	ds_write_b64 v141, v[138:139] offset:8992
	v_mov_b32_e32 v0, v143
	v_pk_mul_f32 v[138:139], v[110:111], v[0:1] op_sel_hi:[1,0]
	v_pk_mul_f32 v[130:131], v[112:113], v[0:1] op_sel_hi:[1,0]
	s_nop 0
	v_cvt_pk_bf16_f32 v138, v138, v139
	s_nop 0
	s_nop 0
	v_cvt_pk_bf16_f32 v139, v130, v131
	ds_write_b64 v137, v[138:139] offset:320
	v_mov_b32_e32 v0, v144
	v_pk_mul_f32 v[138:139], v[78:79], v[0:1] op_sel_hi:[1,0]
	v_pk_mul_f32 v[130:131], v[80:81], v[0:1] op_sel_hi:[1,0]
	s_nop 0
	v_cvt_pk_bf16_f32 v138, v138, v139
	s_nop 0
	s_nop 0
	v_cvt_pk_bf16_f32 v139, v130, v131
	ds_write_b64 v137, v[138:139] offset:9024
	v_mov_b32_e32 v0, v145
	v_pk_mul_f32 v[138:139], v[46:47], v[0:1] op_sel_hi:[1,0]
	v_pk_mul_f32 v[130:131], v[48:49], v[0:1] op_sel_hi:[1,0]
	s_nop 0
	v_cvt_pk_bf16_f32 v138, v138, v139
	s_nop 0
	s_nop 0
	v_cvt_pk_bf16_f32 v139, v130, v131
	ds_write_b64 v140, v[138:139] offset:61248
	v_mov_b32_e32 v0, v146
	v_pk_mul_f32 v[138:139], v[14:15], v[0:1] op_sel_hi:[1,0]
	v_pk_mul_f32 v[130:131], v[16:17], v[0:1] op_sel_hi:[1,0]
	s_nop 0
	v_cvt_pk_bf16_f32 v138, v138, v139
	s_nop 0
	s_nop 0
	v_cvt_pk_bf16_f32 v139, v130, v131
	ds_write_b64 v141, v[138:139] offset:9024
	v_mov_b32_e32 v0, v143
	v_pk_mul_f32 v[138:139], v[106:107], v[0:1] op_sel_hi:[1,0]
	v_pk_mul_f32 v[130:131], v[108:109], v[0:1] op_sel_hi:[1,0]
	s_nop 0
	v_cvt_pk_bf16_f32 v138, v138, v139
	s_nop 0
	s_nop 0
	v_cvt_pk_bf16_f32 v139, v130, v131
	ds_write_b64 v137, v[138:139] offset:352
	v_mov_b32_e32 v0, v144
	v_pk_mul_f32 v[138:139], v[74:75], v[0:1] op_sel_hi:[1,0]
	v_pk_mul_f32 v[130:131], v[76:77], v[0:1] op_sel_hi:[1,0]
	s_nop 0
	v_cvt_pk_bf16_f32 v138, v138, v139
	s_nop 0
	s_nop 0
	v_cvt_pk_bf16_f32 v139, v130, v131
	ds_write_b64 v137, v[138:139] offset:9056
	v_mov_b32_e32 v0, v145
	v_and_b32_e32 v137, 0xff, v132
	v_pk_mul_f32 v[138:139], v[42:43], v[0:1] op_sel_hi:[1,0]
	v_pk_mul_f32 v[130:131], v[44:45], v[0:1] op_sel_hi:[1,0]
	s_nop 0
	v_cvt_pk_bf16_f32 v138, v138, v139
	s_nop 0
	s_nop 0
	v_cvt_pk_bf16_f32 v139, v130, v131
	ds_write_b64 v140, v[138:139] offset:61280
	v_mov_b32_e32 v0, v146
	v_pk_mul_f32 v[130:131], v[8:9], v[0:1] op_sel_hi:[1,0]
	v_pk_mul_f32 v[138:139], v[6:7], v[0:1] op_sel_hi:[1,0]
	v_ashrrev_i32_e32 v0, 5, v132
	s_nop 0
	v_cvt_pk_bf16_f32 v138, v138, v139
	s_nop 0
	v_cvt_pk_bf16_f32 v139, v130, v131
	v_and_b32_e32 v130, -8, v0
	v_lshrrev_b32_e32 v0, 3, v0
	v_mul_lo_u32 v0, v0, s3
	s_sub_i32 s3, s36, s38
	s_sub_i32 s3, s3, s37
	s_sext_i32_i16 s3, s3
	s_add_i32 s2, s2, s3
	s_addk_i32 s2, 0xff80
	s_ashr_i32 s3, s2, 31
	s_lshl_b64 s[2:3], s[2:3], 19
	ds_write_b64 v141, v[138:139] offset:9056
	v_lshlrev_b32_e32 v138, 1, v137
	s_or_b32 s2, s2, s5
	v_ashrrev_i32_e32 v131, 31, v130
	v_add3_u32 v0, v0, v138, 0
	v_lshl_or_b32 v138, v137, 10, s2
	v_mov_b32_e32 v139, s3
	v_lshl_add_u64 v[130:131], v[130:131], 1, v[138:139]
	v_lshl_add_u64 v[130:131], s[10:11], 0, v[130:131]
	s_mov_b32 s2, 0
	s_waitcnt lgkmcnt(0)
	s_barrier
